# XCD-local sync at the four row-local GEMM seams (no L2 write-back / cross-XCD level) when run-time check shows blockIdx%8 classes each sit on one XCC and grid==256, else full barriers; B7 skip guarded
# speedup vs baseline: 1.0982x; 1.0224x over previous
.LBB0_4:
	s_load_dwordx16 s[36:51], s[0:1], 0x0
	v_cndmask_b32_e64 v2, 0, 1, s[4:5]
	v_cmp_ne_u32_e64 s[8:9], 1, v2
	s_add_u32 s68, s74, 0xfa00000
	s_waitcnt lgkmcnt(0)
	v_writelane_b32 v254, s36, 6
	s_barrier
	s_nop 0
	v_writelane_b32 v254, s37, 7
	v_writelane_b32 v254, s38, 8
	v_writelane_b32 v254, s39, 9
	v_writelane_b32 v254, s40, 10
	v_writelane_b32 v254, s41, 11
	v_writelane_b32 v254, s42, 12
	v_writelane_b32 v254, s43, 13
	v_writelane_b32 v254, s44, 14
	v_writelane_b32 v254, s45, 15
	v_writelane_b32 v254, s46, 16
	v_writelane_b32 v254, s47, 17
	v_writelane_b32 v254, s48, 18
	v_writelane_b32 v254, s49, 19
	v_writelane_b32 v254, s50, 20
	v_writelane_b32 v254, s51, 21
	s_getreg_b32 s2, hwreg(HW_REG_XCC_ID, 0, 4)
	v_writelane_b32 v254, s8, 22
	s_addc_u32 s69, s75, 0
	s_and_b32 s2, s2, 15
	v_writelane_b32 v254, s9, 23
	s_andn2_b64 vcc, exec, s[4:5]
	v_writelane_b32 v254, s2, 24
	s_cbranch_vccnz .LBB0_9
	v_mbcnt_lo_u32_b32 v2, -1, 0
	v_mbcnt_hi_u32_b32 v2, -1, v2
	s_nop 0
	v_cmp_eq_u32_e32 vcc, 0, v2
	s_and_saveexec_b64 s[4:5], vcc
	s_cbranch_execz .LBB0_8
	s_mov_b64 s[8:9], exec
	v_mbcnt_lo_u32_b32 v2, s8, 0
	v_mbcnt_hi_u32_b32 v2, s9, v2
	v_cmp_eq_u32_e32 vcc, 0, v2
	s_and_b64 s[2:3], exec, vcc
	s_mov_b64 exec, s[2:3]
	s_cbranch_execz .LBB0_8
	v_readlane_b32 s2, v254, 24
	s_lshl_b32 s2, s2, 8
	s_bcnt1_i32_b64 s3, s[8:9]
	v_mov_b32_e32 v2, s2
	v_mov_b32_e32 v3, s3
	global_atomic_add v2, v3, s[68:69] offset:1024
	s_and_b32 s98, s67, 7
	s_lshl_b32 s98, s98, 2
	s_add_i32 s98, s98, 0xc000
	v_readlane_b32 s99, v254, 24
	s_nop 3
	s_lshl_b32 s99, 1, s99
	v_mov_b32_e32 v4, s98
	v_mov_b32_e32 v5, s99
	global_atomic_or v4, v5, s[68:69]

.LBB0_281:
	s_add_u32 s0, s74, 0x4600000
	s_addc_u32 s1, s75, 0
	s_add_u32 s50, s74, 0x2600000
	s_addc_u32 s51, s75, 0
	v_writelane_b32 v254, s0, 45
	s_add_u32 s4, s74, 0x20000
	s_addc_u32 s5, s75, 0
	v_writelane_b32 v254, s1, 46
	s_add_u32 s6, s74, 0x100000
	v_readlane_b32 s1, v254, 5
	s_addc_u32 s7, s75, 0
	s_bfe_u32 s2, s1, 0x20006
	v_readlane_b32 s0, v254, 25
	s_lshr_b32 s1, s1, 8
	s_lshl_b32 s14, s0, 10
	s_lshl_b32 s0, s1, 6
	v_writelane_b32 v254, s0, 47
	v_writelane_b32 v254, s1, 48
	s_lshl_b32 s0, s1, 13
	v_writelane_b32 v254, s0, 49
	s_lshl_b32 s0, s2, 5
	v_writelane_b32 v254, s0, 50
	s_waitcnt lgkmcnt(0)
	s_barrier
	s_add_u32 s100, s74, 0xfa0c000
	s_addc_u32 s101, s75, 0
	v_mbcnt_lo_u32_b32 v0, -1, 0
	v_mbcnt_hi_u32_b32 v0, -1, v0
	v_and_b32_e32 v0, 7, v0
	v_lshlrev_b32_e32 v0, 2, v0
	global_load_dword v1, v0, s[100:101] sc1
	s_waitcnt vmcnt(0)
	v_bcnt_u32_b32 v1, v1, 0
	v_cmp_ne_u32_e32 vcc, 1, v1
	s_nop 3
	s_cmp_eq_u64 vcc, 0
	s_cselect_b32 s98, 1, 0
	s_cmp_eq_u32 s78, 0x100
	s_cselect_b32 s98, s98, 0
	v_writelane_b32 v254, s1, 51
	v_writelane_b32 v254, s2, 52
	s_lshl_b32 s0, s2, 12
	v_writelane_b32 v254, s0, 53
	v_writelane_b32 v254, s14, 54
	v_writelane_b32 v254, s50, 55
	s_cmpk_gt_i32 s67, 0x27f
	s_nop 0
	v_writelane_b32 v254, s51, 56
	v_writelane_b32 v254, s70, 57
	v_mbcnt_lo_u32_b32 v10, -1, 0
	v_mbcnt_hi_u32_b32 v10, -1, v10
	s_nop 1
	v_writelane_b32 v254, s71, 58
	s_cbranch_scc1 .LBB0_305
	v_lshlrev_b32_e32 v12, 4, v10
	v_add_u32_e32 v0, s14, v12
	v_add_u32_e32 v1, 0x2000, v0
	v_ashrrev_i32_e32 v2, 31, v1
	v_lshrrev_b32_e32 v2, 22, v2
	v_add_u32_e32 v2, v1, v2
	v_ashrrev_i32_e32 v8, 10, v2
	v_mul_i32_i24_e32 v2, 0x400, v8
	v_sub_u32_e32 v1, v1, v2
	v_lshrrev_b32_e32 v2, 4, v1
	v_bitop3_b32 v1, v2, v1, 32 bitop3:0x6c
	v_ashrrev_i32_e32 v2, 31, v1
	v_lshrrev_b32_e32 v2, 26, v2
	v_add_u32_e32 v2, v1, v2
	v_ashrrev_i32_e32 v9, 6, v2
	v_lshlrev_b32_e32 v3, 3, v8
	v_and_b32_e32 v2, 0xffc0, v2
	v_and_b32_e32 v3, -16, v3
	v_sub_u32_e32 v1, v1, v2
	v_add_u32_e32 v3, v9, v3
	v_lshrrev_b16_e32 v2, 7, v1
	v_and_b32_e32 v4, 3, v9
	s_mov_b32 s0, 0x1fffe0
	v_lshrrev_b32_e32 v5, 2, v3
	v_lshlrev_b32_e32 v6, 1, v3
	v_and_b32_e32 v2, 1, v2
	v_and_or_b32 v4, v3, s0, v4
	v_and_b32_e32 v5, 4, v5
	v_and_b32_e32 v6, 24, v6
	v_add_u16_e32 v1, v1, v2
	v_mov_b32_e32 v2, 1
	v_or3_b32 v4, v4, v5, v6
	v_lshlrev_b32_e32 v5, 5, v8
	v_ashrrev_i16_sdwa v1, v2, sext(v1) dst_sel:DWORD dst_unused:UNUSED_PAD src0_sel:DWORD src1_sel:BYTE_0
	v_and_b32_e32 v5, 32, v5
	v_bfe_i32 v11, v1, 0, 16
	v_add_lshl_u32 v1, v5, v11, 1
	v_lshl_add_u32 v128, v4, 11, v1
	v_lshl_add_u32 v130, v3, 11, v1
	v_ashrrev_i32_e32 v1, 31, v0
	v_lshrrev_b32_e32 v1, 22, v1
	v_add_u32_e32 v1, v0, v1
	v_ashrrev_i32_e32 v13, 10, v1
	v_mul_i32_i24_e32 v1, 0x400, v13
	v_sub_u32_e32 v0, v0, v1
	v_lshrrev_b32_e32 v1, 4, v0
	v_bitop3_b32 v0, v1, v0, 32 bitop3:0x6c
	v_ashrrev_i32_e32 v1, 31, v0
	v_lshrrev_b32_e32 v1, 26, v1
	v_add_u32_e32 v1, v0, v1
	v_lshlrev_b32_e32 v3, 3, v13
	s_add_u32 s2, s74, 0x300000
	v_ashrrev_i32_e32 v14, 6, v1
	v_and_b32_e32 v3, -16, v3
	s_addc_u32 s3, s75, 0
	v_add_u32_e32 v3, v14, v3
	v_and_b32_e32 v4, 3, v14
	s_ashr_i32 s33, s67, 31
	v_and_or_b32 v4, v3, s0, v4
	s_lshr_b32 s0, s33, 29
	s_add_i32 s0, s67, s0
	s_ashr_i32 s1, s0, 3
	s_and_b32 s0, s0, -8
	s_sub_i32 s0, s67, s0
	s_cmp_lt_i32 s0, 0
	s_movk_i32 s34, 0x51
	s_cselect_b32 s8, s34, 0x50
	s_mul_i32 s0, s0, s8
	s_add_i32 s0, s0, s1
	s_mul_hi_i32 s1, s0, 0x66666667
	s_lshr_b32 s8, s1, 31
	s_ashr_i32 s1, s1, 5
	s_add_i32 s1, s1, s8
	s_lshl_b32 s8, s1, 3
	s_mulk_i32 s1, 0x50
	s_sub_i32 s1, s0, s1
	s_bfe_i32 s0, s1, 0x80000
	s_bfe_u32 s0, s0, 0x3000c
	s_add_i32 s9, s1, s0
	s_bfe_i32 s0, s9, 0x80000
	s_and_b32 s9, s9, 0xf8
	s_sub_i32 s1, s1, s9
	s_sext_i32_i16 s0, s0
	s_sext_i32_i8 s1, s1
	v_lshrrev_b32_e32 v5, 2, v3
	v_lshlrev_b32_e32 v6, 1, v3
	v_and_b32_e32 v1, 0xc0, v1
	s_lshr_b32 s0, s0, 3
	s_add_i32 s8, s8, s1
	v_and_b32_e32 v5, 4, v5
	v_and_b32_e32 v6, 24, v6
	v_sub_u32_e32 v0, v0, v1
	s_ashr_i32 s9, s8, 31
	s_bfe_i64 s[10:11], s[0:1], 0x100000
	v_or3_b32 v4, v4, v5, v6
	v_lshlrev_b32_e32 v5, 5, v13
	v_ashrrev_i16_sdwa v0, v2, sext(v0) dst_sel:DWORD dst_unused:UNUSED_PAD src0_sel:DWORD src1_sel:BYTE_0
	s_lshl_b64 s[12:13], s[8:9], 19
	s_lshl_b64 s[10:11], s[10:11], 19
	v_and_b32_e32 v5, 32, v5
	v_bfe_i32 v15, v0, 0, 16
	s_add_u32 s10, s2, s10
	v_add_lshl_u32 v0, v5, v15, 1
	s_addc_u32 s11, s3, s11
	s_add_i32 s35, s14, 0
	v_lshl_add_u32 v132, v4, 11, v0
	s_add_i32 m0, s35, 0x10000
	v_lshl_add_u32 v134, v3, 11, v0
	global_load_lds_dwordx4 v132, s[10:11]
	s_add_i32 m0, s35, 0x12000
	s_add_u32 s14, s10, 0x40000
	global_load_lds_dwordx4 v128, s[10:11]
	s_addc_u32 s15, s11, 0
	s_add_i32 m0, s35, 0x14000
	v_mov_b32_e32 v137, 0
	global_load_lds_dwordx4 v132, s[14:15]
	s_add_i32 m0, s35, 0x16000
	s_add_u32 s28, s50, s12
	s_addc_u32 s29, s51, s13
	s_add_i32 s36, s35, 0x2000
	global_load_lds_dwordx4 v128, s[14:15]
	s_mov_b32 m0, s35
	s_add_u32 s12, s28, 0x40000
	global_load_lds_dwordx4 v134, s[28:29]
	s_mov_b32 m0, s36
	s_addc_u32 s13, s29, 0
	s_add_i32 s37, s35, 0x4000
	global_load_lds_dwordx4 v130, s[28:29]
	s_mov_b32 m0, s37
	s_add_i32 s38, s35, 0x6000
	global_load_lds_dwordx4 v134, s[12:13]
	s_mov_b32 m0, s38
	v_readlane_b32 s1, v254, 48
	global_load_lds_dwordx4 v130, s[12:13]
	v_mov_b32_e32 v133, v137
	v_mov_b32_e32 v129, v137
	v_mov_b32_e32 v135, v137
	v_mov_b32_e32 v131, v137
	s_cmp_eq_u32 s1, 1
	s_mov_b32 s9, 0
	v_lshl_add_u64 v[4:5], s[10:11], 0, v[132:133]
	v_lshl_add_u64 v[2:3], s[10:11], 0, v[128:129]
	v_lshl_add_u64 v[0:1], s[28:29], 0, v[134:135]
	s_cselect_b64 s[12:13], -1, 0
	s_cmp_lg_u32 s1, 1
	v_lshl_add_u64 v[6:7], s[28:29], 0, v[130:131]
	s_cbranch_scc1 .LBB0_284
	s_barrier

.LBB0_594:
	s_lshl_b32 s0, s33, 1
	v_readlane_b32 s1, v254, 48
	s_add_i32 s82, s0, s1
	s_bfe_u32 s6, s82, 0x30006
	v_cvt_f32_ubyte0_e32 v0, s6
	v_sub_f32_e32 v0, 0xc0a00000, v0
	s_ashr_i32 s0, s82, 9
	v_cmp_gt_f32_e32 vcc, s10, v0
	s_ashr_i32 s1, s0, 31
	s_lshl_b64 s[68:69], s[0:1], 13
	v_cndmask_b32_e32 v1, 0, v197, vcc
	s_lshl_b32 s0, s82, 7
	v_add_f32_e32 v0, v0, v1
	s_and_b32 s0, s0, 0x1f80
	v_exp_f32_e32 v0, v0
	s_or_b32 s68, s68, s0
	s_and_b64 s[0:1], vcc, exec
	s_cselect_b32 s0, 0xffffffc0, 0
	v_ldexp_f32 v64, v0, s0
	v_sub_f32_e32 v2, 1.0, v64
	v_add_f32_e32 v0, -1.0, v2
	v_sub_f32_e32 v1, v0, v2
	v_add_f32_e32 v1, 1.0, v1
	v_sub_f32_e64 v0, -v64, v0
	v_add_f32_e32 v3, v0, v1
	v_frexp_mant_f32_e32 v4, v2
	v_cvt_f64_f32_e32 v[0:1], v2
	s_mov_b32 s0, 0x3f2aaaab
	v_frexp_exp_i32_f64_e32 v0, v[0:1]
	v_cmp_gt_f32_e32 vcc, s0, v4
	s_lshl_b32 s40, s6, 6
	s_lshl_b32 s60, s6, 7
	v_subbrev_co_u32_e32 v65, vcc, 0, v0, vcc
	v_sub_u32_e32 v0, 0, v65
	v_ldexp_f32 v1, v2, v0
	v_add_f32_e32 v2, -1.0, v1
	v_add_f32_e32 v5, 1.0, v1
	v_ldexp_f32 v0, v3, v0
	v_add_f32_e32 v3, 1.0, v2
	v_add_f32_e32 v6, -1.0, v5
	v_sub_f32_e32 v3, v1, v3
	v_sub_f32_e32 v1, v1, v6
	v_add_f32_e32 v3, v0, v3
	v_add_f32_e32 v0, v0, v1
	v_add_f32_e32 v1, v5, v0
	v_rcp_f32_e32 v66, v1
	v_add_f32_e32 v4, v2, v3
	v_sub_f32_e32 v2, v4, v2
	v_sub_f32_e32 v2, v3, v2
	v_sub_f32_e32 v3, v1, v5
	v_mul_f32_e32 v67, v4, v66
	v_sub_f32_e32 v0, v0, v3
	v_mul_f32_e32 v3, v1, v67
	v_fma_f32 v5, v67, v1, -v3
	v_fmac_f32_e32 v5, v67, v0
	v_add_f32_e32 v6, v3, v5
	v_sub_f32_e32 v68, v4, v6
	v_sub_f32_e32 v4, v4, v68
	v_sub_f32_e32 v3, v6, v3
	v_sub_f32_e32 v4, v4, v6
	v_add_f32_e32 v2, v2, v4
	v_sub_f32_e32 v3, v3, v5
	v_add_f32_e32 v69, v3, v2
	v_add_f32_e32 v70, v68, v69
	s_or_b32 s6, s40, 0x200
	v_mul_f32_e32 v71, v66, v70
	v_add_u32_e32 v8, s6, v161
	v_mul_f32_e32 v72, v1, v71
	v_ashrrev_i32_e32 v9, 31, v8
	v_fma_f32 v73, v71, v1, -v72
	v_lshl_add_u64 v[60:61], s[68:69], 1, v[132:133]
	v_lshlrev_b64 v[8:9], 15, v[8:9]
	v_add_u32_e32 v26, s6, v162
	v_add_u32_e32 v40, s6, v163
	v_fmac_f32_e32 v73, v71, v0
	v_lshl_add_u64 v[44:45], v[130:131], 0, s[60:61]
	v_lshl_add_u64 v[0:1], s[68:69], 0, v[136:137]
	v_lshl_add_u64 v[24:25], v[60:61], 0, v[8:9]
	v_lshl_add_u64 v[8:9], s[68:69], 0, v[138:139]
	v_ashrrev_i32_e32 v27, 31, v26
	v_lshl_add_u64 v[32:33], s[68:69], 0, v[140:141]
	v_ashrrev_i32_e32 v41, 31, v40
	v_lshl_add_u64 v[46:47], s[68:69], 0, v[142:143]
	v_mad_u64_u32 v[16:17], s[0:1], v0, s11, v[44:45]
	v_mad_u64_u32 v[20:21], s[0:1], v8, s11, v[44:45]
	v_lshlrev_b64 v[26:27], 15, v[26:27]
	v_mad_u64_u32 v[52:53], s[0:1], v32, s11, v[44:45]
	v_lshlrev_b64 v[40:41], 15, v[40:41]
	v_mad_u64_u32 v[56:57], s[0:1], v46, s11, v[44:45]
	v_mad_i32_i24 v17, v1, s11, v17
	v_mad_i32_i24 v21, v9, s11, v21
	v_lshl_add_u64 v[28:29], v[60:61], 0, v[26:27]
	v_mad_i32_i24 v53, v33, s11, v53
	v_lshl_add_u64 v[40:41], v[60:61], 0, v[40:41]
	v_mad_i32_i24 v57, v47, s11, v57
	s_barrier
	global_load_dwordx4 v[0:3], v[16:17], off offset:1024 nt
	global_load_dwordx4 v[4:7], v[16:17], off offset:2048 nt
	global_load_dwordx4 v[8:11], v[20:21], off nt
	global_load_dwordx4 v[12:15], v[20:21], off offset:1024 nt
	s_nop 0
	global_load_dwordx4 v[16:19], v[16:17], off nt
	s_nop 0
	global_load_dwordx4 v[20:23], v[20:21], off offset:2048 nt
	s_nop 0
	global_load_dwordx4 v[24:27], v[24:25], off nt
	s_nop 0
	global_load_dwordx4 v[28:31], v[28:29], off nt
	s_nop 0
	global_load_dwordx4 v[32:35], v[52:53], off offset:1024 nt
	global_load_dwordx4 v[36:39], v[52:53], off offset:2048 nt
	v_add_u32_e32 v62, s6, v164
	global_load_dwordx4 v[40:43], v[40:41], off nt
	s_nop 0
	global_load_dwordx4 v[44:47], v[56:57], off nt
	global_load_dwordx4 v[48:51], v[56:57], off offset:1024 nt
	s_nop 0
	global_load_dwordx4 v[52:55], v[52:53], off nt
	s_nop 0
	global_load_dwordx4 v[56:59], v[56:57], off offset:2048 nt
	v_ashrrev_i32_e32 v63, 31, v62
	v_lshlrev_b64 v[62:63], 15, v[62:63]
	v_lshl_add_u64 v[60:61], v[60:61], 0, v[62:63]
	global_load_dwordx4 v[60:63], v[60:61], off nt
	v_sub_f32_e32 v68, v68, v70
	v_add_f32_e32 v68, v69, v68
	v_add_f32_e32 v69, v72, v73
	v_sub_f32_e32 v74, v70, v69
	v_sub_f32_e32 v70, v70, v74
	v_sub_f32_e32 v72, v69, v72
	v_sub_f32_e32 v69, v70, v69
	v_add_f32_e32 v68, v68, v69
	v_sub_f32_e32 v69, v72, v73
	v_add_f32_e32 v68, v69, v68
	v_add_f32_e32 v68, v74, v68
	v_cvt_f32_i32_e32 v65, v65
	v_mul_f32_e32 v66, v66, v68
	v_add_f32_e32 v68, v67, v71
	v_sub_f32_e32 v67, v68, v67
	v_sub_f32_e32 v67, v71, v67
	v_add_f32_e32 v66, v67, v66
	v_mul_f32_e32 v71, 0x3f317218, v65
	s_mov_b32 s0, 0x3f317218
	v_add_f32_e32 v67, v68, v66
	v_fma_f32 v72, v65, s0, -v71
	v_mul_f32_e32 v69, v67, v67
	v_fmac_f32_e32 v72, 0xb102e308, v65
	v_sub_f32_e32 v65, v67, v68
	v_fmamk_f32 v70, v69, 0x3e9b6dac, v169
	v_sub_f32_e32 v65, v66, v65
	v_add_f32_e32 v66, v71, v72
	v_fmaak_f32 v70, v69, v70, 0x3f2aaada
	v_sub_f32_e32 v68, v66, v71
	v_ldexp_f32 v71, v67, 1
	v_mul_f32_e32 v67, v67, v69
	v_mul_f32_e32 v67, v67, v70
	v_add_f32_e32 v69, v71, v67
	v_sub_f32_e32 v70, v69, v71
	v_ldexp_f32 v65, v65, 1
	v_sub_f32_e32 v67, v67, v70
	v_add_f32_e32 v65, v65, v67
	v_add_f32_e32 v67, v69, v65
	v_sub_f32_e32 v69, v67, v69
	v_sub_f32_e32 v65, v65, v69
	v_add_f32_e32 v69, v66, v67
	v_sub_f32_e32 v70, v69, v66
	v_sub_f32_e32 v71, v69, v70
	v_sub_f32_e32 v68, v72, v68
	v_sub_f32_e32 v66, v66, v71
	v_sub_f32_e32 v67, v67, v70
	v_add_f32_e32 v66, v67, v66
	v_add_f32_e32 v67, v68, v65
	v_sub_f32_e32 v70, v67, v68
	v_sub_f32_e32 v71, v67, v70
	v_add_f32_e32 v66, v67, v66
	v_sub_f32_e32 v68, v68, v71
	v_sub_f32_e32 v65, v65, v70
	v_add_f32_e32 v67, v69, v66
	v_add_f32_e32 v65, v65, v68
	v_sub_f32_e32 v68, v67, v69
	v_sub_f32_e32 v66, v66, v68
	v_add_f32_e32 v65, v65, v66
	v_add_f32_e32 v65, v67, v65
	v_cmp_nlt_f32_e32 vcc, 1.0, v64
	s_mov_b32 s0, 0x33800000
	s_waitcnt vmcnt(0)
	ds_write_b128 v170, v[16:19]
	ds_write_b128 v170, v[0:3] offset:16384
	ds_write_b128 v170, v[4:7] offset:32768
	ds_write_b128 v171, v[24:27] offset:49152
	ds_write_b128 v172, v[8:11]
	ds_write_b128 v172, v[12:15] offset:16384
	ds_write_b128 v172, v[20:23] offset:32768
	ds_write_b128 v173, v[28:31] offset:49152
	ds_write_b128 v174, v[52:55]
	ds_write_b128 v174, v[32:35] offset:16384
	ds_write_b128 v174, v[36:39] offset:32768
	ds_write_b128 v175, v[40:43] offset:49152
	ds_write_b128 v176, v[44:47]
	ds_write_b128 v176, v[48:51] offset:16384
	ds_write_b128 v176, v[56:59] offset:32768
	ds_write_b128 v177, v[60:63] offset:49152
	v_cndmask_b32_e32 v65, v198, v65, vcc
	v_cmp_neq_f32_e32 vcc, 1.0, v64
	s_waitcnt lgkmcnt(0)
	s_barrier
	v_cndmask_b32_e32 v65, v199, v65, vcc
	v_cmp_gt_f32_e32 vcc, s0, v64
	v_mov_b32_e32 v48, v154
	s_nop 0
	v_cndmask_b32_e64 v80, v65, -v64, vcc
	ds_read_b128 v[76:79], v178
	ds_read_b128 v[72:75], v179
	ds_read_b128 v[68:71], v180
	ds_read_b128 v[64:67], v181
	v_mul_f32_e32 v201, 0x3fb8aa3b, v80
	v_mov_b32_e32 v49, v153
	s_mov_b32 s41, 0
	v_mov_b32_e32 v16, 0
	v_mov_b32_e32 v17, v129
	v_mov_b32_e32 v18, v129
	v_mov_b32_e32 v19, v129
	v_mov_b32_e32 v20, v129
	v_mov_b32_e32 v21, v129
	v_mov_b32_e32 v22, v129
	v_mov_b32_e32 v23, v129
	v_mov_b32_e32 v24, v129
	v_mov_b32_e32 v25, v129
	v_mov_b32_e32 v26, v129
	v_mov_b32_e32 v27, v129
	v_mov_b32_e32 v28, v129
	v_mov_b32_e32 v29, v129
	v_mov_b32_e32 v30, v129
	v_mov_b32_e32 v31, v129
	v_mov_b32_e32 v0, 0
	v_mov_b32_e32 v1, v129
	v_mov_b32_e32 v2, v129
	v_mov_b32_e32 v3, v129
	v_mov_b32_e32 v4, v129
	v_mov_b32_e32 v5, v129
	v_mov_b32_e32 v6, v129
	v_mov_b32_e32 v7, v129
	v_mov_b32_e32 v8, v129
	v_mov_b32_e32 v9, v129
	v_mov_b32_e32 v10, v129
	v_mov_b32_e32 v11, v129
	v_mov_b32_e32 v12, v129
	v_mov_b32_e32 v13, v129
	v_mov_b32_e32 v14, v129
	v_mov_b32_e32 v15, v129
	s_ashr_i32 s83, s82, 31
	s_lshl_b64 s[0:1], s[82:83], 14
	v_lshl_add_u64 v[244:245], v[150:151], 0, s[0:1]
	s_mov_b64 s[0:1], 0x2000
	global_load_dwordx4 v[224:227], v[244:245], off nt
	global_load_dwordx4 v[228:231], v[244:245], off offset:16 nt
	v_lshl_add_u64 v[246:247], v[244:245], 0, s[0:1]
	global_load_dwordx4 v[232:235], v[246:247], off nt
	global_load_dwordx4 v[236:239], v[246:247], off offset:16 nt
	global_load_dwordx4 v[100:103], v[244:245], off offset:64 nt
	global_load_dwordx4 v[88:91], v[244:245], off offset:80 nt
	global_load_dwordx4 v[104:107], v[246:247], off offset:64 nt
	v_lshl_add_u64 v[248:249], v[244:245], 0, s[62:63]
	global_load_dwordx4 v[108:111], v[248:249], off offset:16 nt
	global_load_dwordx4 v[92:95], v[244:245], off offset:128 nt
	global_load_dwordx4 v[240:243], v[244:245], off offset:144 nt
	global_load_dwordx4 v[112:115], v[246:247], off offset:128 nt
	v_lshl_add_u64 v[250:251], v[244:245], 0, s[64:65]
	global_load_dwordx4 v[116:119], v[250:251], off offset:16 nt
	global_load_dwordx4 v[96:99], v[244:245], off offset:192 nt
	global_load_dwordx4 v[84:87], v[244:245], off offset:208 nt
	global_load_dwordx4 v[120:123], v[246:247], off offset:192 nt
	v_lshl_add_u64 v[248:249], v[244:245], 0, s[66:67]
	global_load_dwordx4 v[124:127], v[248:249], off offset:16 nt
.LBB0_595:
	v_add_u32_e32 v32, s41, v168
	ds_read_b128 v[32:35], v32
	v_add_u32_e32 v50, s41, v167
	ds_read_b128 v[50:53], v50
	s_waitcnt lgkmcnt(1)
	v_mfma_f32_32x32x16_bf16 v[32:47], v[32:35], v[76:79], 0
	s_waitcnt lgkmcnt(0)
	v_mfma_f32_32x32x16_bf16 v[32:47], v[50:53], v[72:75], v[32:47]
	v_add_u32_e32 v50, s41, v166
	ds_read_b128 v[50:53], v50
	s_waitcnt lgkmcnt(0)
	v_mfma_f32_32x32x16_bf16 v[32:47], v[50:53], v[68:71], v[32:47]
	v_add_u32_e32 v50, s41, v165
	ds_read_b128 v[50:53], v50
	s_addk_i32 s41, 0x1000
	s_cmp_eq_u32 s3, s41
	s_waitcnt lgkmcnt(0)
	v_mfma_f32_32x32x16_bf16 v[32:47], v[50:53], v[64:67], v[32:47]
	v_add_u32_e32 v51, v48, v135
	v_add_u32_e32 v52, v48, v134
	v_cvt_f32_u32_e32 v50, v52
	v_cmp_lt_i32_e32 vcc, -1, v51
	v_cvt_f32_u32_e32 v51, v51
	v_cmp_lt_i32_e64 s[0:1], -1, v52
	v_mul_f32_e32 v50, v201, v50
	v_exp_f32_e32 v50, v50
	v_mul_f32_e32 v51, v201, v51
	v_exp_f32_e32 v51, v51
	v_add_u32_e32 v52, v48, v144
	v_cmp_lt_i32_e64 s[8:9], -1, v52
	v_pk_mul_f32 v[32:33], v[50:51], v[32:33]
	v_add_u32_e32 v51, v48, v145
	v_cvt_f32_u32_e32 v50, v52
	v_cmp_lt_i32_e64 s[6:7], -1, v51
	v_cvt_f32_u32_e32 v51, v51
	v_add_u32_e32 v52, v48, v146
	v_mul_f32_e32 v50, v201, v50
	v_exp_f32_e32 v50, v50
	v_mul_f32_e32 v51, v201, v51
	v_exp_f32_e32 v51, v51
	v_cmp_lt_i32_e64 s[14:15], -1, v52
	v_cvt_pk_bf16_f32 v32, v32, v33
	v_cndmask_b32_e64 v33, 0, v32, s[0:1]
	v_pk_mul_f32 v[34:35], v[50:51], v[34:35]
	v_add_u32_e32 v51, v48, v147
	v_cvt_f32_u32_e32 v50, v52
	v_cmp_lt_i32_e64 s[12:13], -1, v51
	v_cvt_f32_u32_e32 v51, v51
	v_add_u32_e32 v52, v48, v148
	v_mul_f32_e32 v50, v201, v50
	v_exp_f32_e32 v50, v50
	v_mul_f32_e32 v51, v201, v51
	v_exp_f32_e32 v51, v51
	v_cmp_lt_i32_e64 s[18:19], -1, v52
	v_lshrrev_b32_e32 v32, 16, v32
	v_cndmask_b32_e32 v32, 0, v32, vcc
	v_pk_mul_f32 v[50:51], v[50:51], v[36:37]
	v_add_u32_e32 v37, v48, v149
	v_cvt_f32_u32_e32 v36, v52
	v_cmp_lt_i32_e64 s[16:17], -1, v37
	v_cvt_f32_u32_e32 v37, v37
	v_mul_f32_e32 v36, v201, v36
	v_exp_f32_e32 v36, v36
	v_mul_f32_e32 v37, v201, v37
	v_exp_f32_e32 v37, v37
	s_nop 0
	v_pk_mul_f32 v[52:53], v[36:37], v[38:39]
	v_add_u32_e32 v38, -16, v48
	v_add_u32_e32 v37, v38, v135
	v_add_u32_e32 v39, v38, v134
	v_cvt_f32_u32_e32 v36, v39
	v_cmp_lt_i32_e64 s[22:23], -1, v37
	v_cvt_f32_u32_e32 v37, v37
	v_cmp_lt_i32_e64 s[24:25], -1, v39
	v_mul_f32_e32 v36, v201, v36
	v_exp_f32_e32 v36, v36
	v_mul_f32_e32 v37, v201, v37
	v_exp_f32_e32 v37, v37
	v_add_u32_e32 v39, v38, v144
	v_cmp_lt_i32_e64 s[28:29], -1, v39
	v_subrev_u32_e32 v48, 32, v48
	v_pk_mul_f32 v[40:41], v[36:37], v[40:41]
	v_add_u32_e32 v37, v38, v145
	v_cvt_f32_u32_e32 v36, v39
	v_cmp_lt_i32_e64 s[26:27], -1, v37
	v_cvt_f32_u32_e32 v37, v37
	v_add_u32_e32 v39, v38, v146
	v_mul_f32_e32 v36, v201, v36
	v_exp_f32_e32 v36, v36
	v_mul_f32_e32 v37, v201, v37
	v_exp_f32_e32 v37, v37
	v_cmp_lt_i32_e64 s[34:35], -1, v39
	v_pk_mul_f32 v[42:43], v[36:37], v[42:43]
	v_add_u32_e32 v37, v38, v147
	v_cvt_f32_u32_e32 v36, v39
	v_cmp_lt_i32_e64 s[30:31], -1, v37
	v_cvt_f32_u32_e32 v37, v37
	v_mul_f32_e32 v36, v201, v36
	v_exp_f32_e32 v36, v36
	v_mul_f32_e32 v37, v201, v37
	v_exp_f32_e32 v37, v37
	s_nop 0
	v_pk_mul_f32 v[44:45], v[36:37], v[44:45]
	v_add_u32_e32 v37, v38, v149
	v_add_u32_e32 v38, v38, v148
	v_cvt_f32_u32_e32 v36, v38
	v_cmp_lt_i32_e64 s[36:37], -1, v37
	v_cvt_f32_u32_e32 v37, v37
	v_cmp_lt_i32_e64 s[38:39], -1, v38
	v_mul_f32_e32 v36, v201, v36
	v_exp_f32_e32 v36, v36
	v_mul_f32_e32 v37, v201, v37
	v_exp_f32_e32 v37, v37
	s_nop 0
	v_pk_mul_f32 v[46:47], v[36:37], v[46:47]
	v_perm_b32 v36, v32, v33, s20
	v_cvt_pk_bf16_f32 v32, v34, v35
	v_cndmask_b32_e64 v33, 0, v32, s[8:9]
	v_lshrrev_b32_e32 v32, 16, v32
	v_cndmask_b32_e64 v32, 0, v32, s[6:7]
	v_perm_b32 v37, v32, v33, s20
	v_cvt_pk_bf16_f32 v32, v50, v51
	v_cndmask_b32_e64 v33, 0, v32, s[14:15]
	v_lshrrev_b32_e32 v32, 16, v32
	v_cndmask_b32_e64 v32, 0, v32, s[12:13]
	v_perm_b32 v38, v32, v33, s20
	v_cvt_pk_bf16_f32 v32, v52, v53
	v_cndmask_b32_e64 v33, 0, v32, s[18:19]
	v_lshrrev_b32_e32 v32, 16, v32
	v_cndmask_b32_e64 v32, 0, v32, s[16:17]
	v_perm_b32 v39, v32, v33, s20
	v_cvt_pk_bf16_f32 v32, v40, v41
	v_cndmask_b32_e64 v33, 0, v32, s[24:25]
	v_lshrrev_b32_e32 v32, 16, v32
	v_cndmask_b32_e64 v32, 0, v32, s[22:23]
	v_perm_b32 v32, v32, v33, s20
	v_cvt_pk_bf16_f32 v33, v42, v43
	v_cndmask_b32_e64 v34, 0, v33, s[28:29]
	v_lshrrev_b32_e32 v33, 16, v33
	v_cndmask_b32_e64 v33, 0, v33, s[26:27]
	v_perm_b32 v33, v33, v34, s20
	v_cvt_pk_bf16_f32 v34, v44, v45
	v_cndmask_b32_e64 v35, 0, v34, s[34:35]
	v_lshrrev_b32_e32 v34, 16, v34
	v_cndmask_b32_e64 v34, 0, v34, s[30:31]
	v_perm_b32 v34, v34, v35, s20
	v_cvt_pk_bf16_f32 v35, v46, v47
	v_cndmask_b32_e64 v40, 0, v35, s[38:39]
	v_lshrrev_b32_e32 v35, 16, v35
	v_cndmask_b32_e64 v35, 0, v35, s[36:37]
	v_perm_b32 v35, v35, v40, s20
	v_xor_b32_e32 v40, v49, v156
	v_add_u32_e32 v41, 2, v49
	v_lshl_add_u32 v45, v40, 4, v155
	v_xor_b32_e32 v44, v41, v156
	ds_read_b128 v[40:43], v45 offset:49152
	v_lshl_add_u32 v44, v44, 4, v155
	s_waitcnt lgkmcnt(0)
	v_mfma_f32_32x32x16_bf16 v[16:31], v[40:43], v[36:39], v[16:31]
	ds_read_b128 v[40:43], v44 offset:49152
	v_add_u32_e32 v49, 4, v49
	s_waitcnt lgkmcnt(0)
	v_mfma_f32_32x32x16_bf16 v[16:31], v[40:43], v[32:35], v[16:31]
	ds_read_b128 v[40:43], v45 offset:57344
	s_waitcnt lgkmcnt(0)
	v_mfma_f32_32x32x16_bf16 v[0:15], v[40:43], v[36:39], v[0:15]
	ds_read_b128 v[36:39], v44 offset:57344
	s_waitcnt lgkmcnt(0)
	v_mfma_f32_32x32x16_bf16 v[0:15], v[36:39], v[32:35], v[0:15]
	s_cbranch_scc0 .LBB0_595
	s_nop 7
	v_mul_f32_e32 v48, v201, v157
	v_add_u32_e32 v49, v158, v160
	v_cmp_gt_f32_e32 vcc, s10, v48
	ds_read_b64 v[202:203], v185 offset:32768
	ds_read_b64 v[204:205], v186 offset:32768
	ds_read_b64 v[206:207], v187 offset:32768
	ds_read_b64 v[208:209], v188 offset:32768
	ds_read_b64 v[210:211], v49 offset:32768
	ds_read_b64 v[212:213], v182 offset:32768
	ds_read_b64 v[214:215], v183 offset:32768
	ds_read_b64 v[216:217], v184 offset:32768
	v_cndmask_b32_e32 v222, 0, v200, vcc
	s_waitcnt lgkmcnt(3)
	v_lshlrev_b32_e32 v220, 16, v210
	v_and_b32_e32 v221, 0xffff0000, v210
	v_lshlrev_b32_e32 v218, 16, v202
	v_and_b32_e32 v219, 0xffff0000, v202
	s_or_b64 s[0:1], s[68:69], s[42:43]
	s_lshl_b64 s[0:1], s[0:1], 11
	v_readlane_b32 s6, v255, 4
	s_add_u32 s0, s6, s0
	v_readlane_b32 s6, v255, 5
	s_addc_u32 s1, s6, s1
	s_lshl_b32 s6, s40, 1
	s_add_u32 s0, s0, s6
	s_addc_u32 s1, s1, 0
	s_add_i32 s33, s33, s78
	s_cmpk_gt_i32 s33, 0x1ff
	s_waitcnt vmcnt(15)
	v_cvt_pk_bf16_f32 v32, v224, v225
	v_cvt_pk_bf16_f32 v33, v226, v227
	s_waitcnt vmcnt(14)
	v_cvt_pk_bf16_f32 v34, v228, v229
	v_cvt_pk_bf16_f32 v35, v230, v231
	s_waitcnt vmcnt(12)
	v_cvt_pk_bf16_f32 v38, v236, v237
	v_cvt_pk_bf16_f32 v36, v232, v233
	v_cvt_pk_bf16_f32 v37, v234, v235
	v_cvt_pk_bf16_f32 v39, v238, v239
	v_mfma_f32_32x32x16_bf16 v[48:63], v[32:35], v[76:79], 0
	v_cndmask_b32_e32 v32, 0, v197, vcc
	v_fmac_f32_e32 v32, v201, v157
	v_exp_f32_e32 v201, v32
	s_waitcnt vmcnt(11)
	v_cvt_pk_bf16_f32 v100, v100, v101
	v_cvt_pk_bf16_f32 v101, v102, v103
	s_waitcnt vmcnt(10)
	v_cvt_pk_bf16_f32 v102, v88, v89
	v_cvt_pk_bf16_f32 v103, v90, v91
	v_mfma_f32_32x32x16_bf16 v[32:47], v[36:39], v[76:79], 0
	s_waitcnt vmcnt(9)
	v_cvt_pk_bf16_f32 v76, v104, v105
	v_cvt_pk_bf16_f32 v77, v106, v107
	s_waitcnt vmcnt(8)
	v_cvt_pk_bf16_f32 v78, v108, v109
	v_cvt_pk_bf16_f32 v79, v110, v111
	s_waitcnt vmcnt(7)
	v_cvt_pk_bf16_f32 v88, v92, v93
	v_cvt_pk_bf16_f32 v89, v94, v95
	s_waitcnt vmcnt(6)
	v_cvt_pk_bf16_f32 v90, v240, v241
	v_mfma_f32_32x32x16_bf16 v[48:63], v[100:103], v[72:75], v[48:63]
	v_cvt_pk_bf16_f32 v91, v242, v243
	v_lshlrev_b32_e32 v100, 16, v211
	v_and_b32_e32 v101, 0xffff0000, v211
	s_waitcnt lgkmcnt(2)
	v_lshlrev_b32_e32 v80, 16, v212
	v_and_b32_e32 v81, 0xffff0000, v212
	v_lshlrev_b32_e32 v82, 16, v213
	v_and_b32_e32 v83, 0xffff0000, v213
	v_mfma_f32_32x32x16_bf16 v[32:47], v[76:79], v[72:75], v[32:47]
	s_waitcnt vmcnt(5)
	v_cvt_pk_bf16_f32 v72, v112, v113
	v_cvt_pk_bf16_f32 v73, v114, v115
	s_waitcnt vmcnt(4)
	v_cvt_pk_bf16_f32 v74, v116, v117
	v_cvt_pk_bf16_f32 v75, v118, v119
	s_waitcnt vmcnt(3)
	v_cvt_pk_bf16_f32 v76, v96, v97
	v_cvt_pk_bf16_f32 v77, v98, v99
	s_waitcnt vmcnt(2)
	v_cvt_pk_bf16_f32 v78, v84, v85
	v_mfma_f32_32x32x16_bf16 v[48:63], v[88:91], v[68:71], v[48:63]
	v_cvt_pk_bf16_f32 v79, v86, v87
	s_waitcnt lgkmcnt(1)
	v_lshlrev_b32_e32 v88, 16, v214
	v_and_b32_e32 v89, 0xffff0000, v214
	v_mfma_f32_32x32x16_bf16 v[32:47], v[72:75], v[68:71], v[32:47]
	s_waitcnt vmcnt(1)
	v_cvt_pk_bf16_f32 v68, v120, v121
	v_cvt_pk_bf16_f32 v69, v122, v123
	s_waitcnt vmcnt(0)
	v_cvt_pk_bf16_f32 v70, v124, v125
	v_cvt_pk_bf16_f32 v71, v126, v127
	v_lshlrev_b32_e32 v72, 16, v215
	v_and_b32_e32 v73, 0xffff0000, v215
	s_waitcnt lgkmcnt(0)
	v_lshlrev_b32_e32 v74, 16, v216
	v_mfma_f32_32x32x16_bf16 v[48:63], v[76:79], v[64:67], v[48:63]
	v_ldexp_f32 v78, v201, v222
	v_and_b32_e32 v75, 0xffff0000, v216
	v_lshlrev_b32_e32 v76, 16, v217
	v_and_b32_e32 v77, 0xffff0000, v217
	v_mfma_f32_32x32x16_bf16 v[32:47], v[68:71], v[64:67], v[32:47]
	s_nop 6
	v_fma_f32 v16, v78, v48, v16
	v_fma_f32 v17, v78, v49, v17
	v_fma_f32 v18, v78, v50, v18
	v_fma_f32 v19, v78, v51, v19
	v_mul_f32_e32 v48, v19, v19
	v_pk_fma_f32 v[20:21], v[78:79], v[52:53], v[20:21] op_sel_hi:[0,1,1]
	v_mul_f32_e32 v50, v21, v21
	v_pk_fma_f32 v[22:23], v[78:79], v[54:55], v[22:23] op_sel_hi:[0,1,1]
	v_mul_f32_e32 v52, v23, v23
	v_pk_fma_f32 v[14:15], v[78:79], v[46:47], v[14:15] op_sel_hi:[0,1,1]
	v_mul_f32_e32 v46, v17, v17
	v_pk_fma_f32 v[0:1], v[78:79], v[32:33], v[0:1] op_sel_hi:[0,1,1]
	v_pk_fma_f32 v[32:33], v[16:17], v[16:17], v[46:47] op_sel_hi:[1,1,0]
	v_pk_fma_f32 v[24:25], v[78:79], v[56:57], v[24:25] op_sel_hi:[0,1,1]
	v_pk_fma_f32 v[32:33], v[18:19], v[18:19], v[32:33]
	v_mul_f32_e32 v54, v25, v25
	v_pk_add_f32 v[32:33], v[48:49], v[32:33] op_sel_hi:[0,1]
	v_pk_fma_f32 v[32:33], v[20:21], v[20:21], v[32:33]
	v_pk_fma_f32 v[26:27], v[78:79], v[58:59], v[26:27] op_sel_hi:[0,1,1]
	v_pk_add_f32 v[32:33], v[50:51], v[32:33] op_sel_hi:[0,1]
	v_pk_fma_f32 v[32:33], v[22:23], v[22:23], v[32:33]
	v_mul_f32_e32 v56, v27, v27
	v_pk_add_f32 v[32:33], v[52:53], v[32:33] op_sel_hi:[0,1]
	v_pk_fma_f32 v[32:33], v[24:25], v[24:25], v[32:33]
	v_pk_fma_f32 v[28:29], v[78:79], v[60:61], v[28:29] op_sel_hi:[0,1,1]
	v_pk_add_f32 v[32:33], v[54:55], v[32:33] op_sel_hi:[0,1]
	v_pk_fma_f32 v[32:33], v[26:27], v[26:27], v[32:33]
	v_mul_f32_e32 v58, v29, v29
	v_pk_add_f32 v[32:33], v[56:57], v[32:33] op_sel_hi:[0,1]
	v_pk_fma_f32 v[32:33], v[28:29], v[28:29], v[32:33]
	v_pk_fma_f32 v[30:31], v[78:79], v[62:63], v[30:31] op_sel_hi:[0,1,1]
	v_pk_add_f32 v[32:33], v[58:59], v[32:33] op_sel_hi:[0,1]
	v_mul_f32_e32 v60, v31, v31
	v_pk_fma_f32 v[32:33], v[30:31], v[30:31], v[32:33]
	v_pk_fma_f32 v[2:3], v[78:79], v[34:35], v[2:3] op_sel_hi:[0,1,1]
	v_pk_add_f32 v[32:33], v[60:61], v[32:33] op_sel_hi:[0,1]
	v_mul_f32_e32 v34, v1, v1
	v_pk_fma_f32 v[32:33], v[0:1], v[0:1], v[32:33]
	v_mul_f32_e32 v46, v3, v3
	v_pk_add_f32 v[32:33], v[34:35], v[32:33] op_sel_hi:[0,1]
	v_pk_fma_f32 v[32:33], v[2:3], v[2:3], v[32:33]
	v_pk_fma_f32 v[4:5], v[78:79], v[36:37], v[4:5] op_sel_hi:[0,1,1]
	v_pk_add_f32 v[32:33], v[46:47], v[32:33] op_sel_hi:[0,1]
	v_pk_fma_f32 v[32:33], v[4:5], v[4:5], v[32:33]
	v_mul_f32_e32 v36, v5, v5
	v_pk_fma_f32 v[6:7], v[78:79], v[38:39], v[6:7] op_sel_hi:[0,1,1]
	v_pk_add_f32 v[32:33], v[36:37], v[32:33] op_sel_hi:[0,1]
	v_pk_fma_f32 v[32:33], v[6:7], v[6:7], v[32:33]
	v_mul_f32_e32 v38, v7, v7
	v_pk_add_f32 v[32:33], v[38:39], v[32:33] op_sel_hi:[0,1]
	v_pk_fma_f32 v[8:9], v[78:79], v[40:41], v[8:9] op_sel_hi:[0,1,1]
	v_pk_fma_f32 v[32:33], v[8:9], v[8:9], v[32:33]
	v_mul_f32_e32 v40, v9, v9
	v_pk_fma_f32 v[10:11], v[78:79], v[42:43], v[10:11] op_sel_hi:[0,1,1]
	v_pk_add_f32 v[32:33], v[40:41], v[32:33] op_sel_hi:[0,1]
	v_pk_fma_f32 v[32:33], v[10:11], v[10:11], v[32:33]
	v_mul_f32_e32 v42, v11, v11
	v_pk_add_f32 v[32:33], v[42:43], v[32:33] op_sel_hi:[0,1]
	v_pk_fma_f32 v[12:13], v[78:79], v[44:45], v[12:13] op_sel_hi:[0,1,1]
	v_pk_fma_f32 v[32:33], v[12:13], v[12:13], v[32:33]
	v_mul_f32_e32 v42, v13, v13
	v_pk_add_f32 v[32:33], v[42:43], v[32:33] op_sel_hi:[0,1]
	v_pk_fma_f32 v[32:33], v[14:15], v[14:15], v[32:33]
	v_mul_f32_e32 v42, v15, v15
	v_pk_add_f32 v[32:33], v[42:43], v[32:33] op_sel_hi:[0,1]
	v_mov_b32_e32 v33, v32
	s_nop 1
	v_permlane32_swap_b32_e32 v32, v33
	v_add_f32_e32 v32, v32, v33
	v_fmamk_f32 v32, v32, 0x3c800000, v189
	v_mul_f32_e32 v33, 0x4b800000, v32
	v_cmp_gt_f32_e32 vcc, s21, v32
	v_lshlrev_b32_e32 v34, 16, v203
	v_and_b32_e32 v35, 0xffff0000, v203
	v_cndmask_b32_e32 v32, v32, v33, vcc
	v_rsq_f32_e32 v42, v32
	v_lshlrev_b32_e32 v36, 16, v204
	v_and_b32_e32 v37, 0xffff0000, v204
	v_lshlrev_b32_e32 v38, 16, v205
	v_mul_f32_e32 v43, 0x45800000, v42
	v_cndmask_b32_e32 v42, v42, v43, vcc
	v_pk_mul_f32 v[16:17], v[16:17], v[42:43] op_sel_hi:[1,0]
	v_pk_mul_f32 v[18:19], v[18:19], v[42:43] op_sel_hi:[1,0]
	v_pk_mul_f32 v[16:17], v[16:17], v[220:221]
	v_pk_mul_f32 v[18:19], v[18:19], v[100:101]
	v_cvt_pk_bf16_f32 v16, v16, v17
	v_cvt_pk_bf16_f32 v17, v18, v19
	v_add_u32_e32 v18, v159, v128
	ds_write_b64 v18, v[16:17]
	v_pk_mul_f32 v[16:17], v[20:21], v[42:43] op_sel_hi:[1,0]
	v_pk_mul_f32 v[18:19], v[22:23], v[42:43] op_sel_hi:[1,0]
	v_pk_mul_f32 v[16:17], v[16:17], v[80:81]
	v_pk_mul_f32 v[18:19], v[18:19], v[82:83]
	v_cvt_pk_bf16_f32 v16, v16, v17
	v_cvt_pk_bf16_f32 v17, v18, v19
	ds_write_b64 v190, v[16:17]
	v_pk_mul_f32 v[16:17], v[24:25], v[42:43] op_sel_hi:[1,0]
	v_pk_mul_f32 v[18:19], v[26:27], v[42:43] op_sel_hi:[1,0]
	v_pk_mul_f32 v[16:17], v[16:17], v[88:89]
	v_pk_mul_f32 v[18:19], v[18:19], v[72:73]
	v_cvt_pk_bf16_f32 v16, v16, v17
	v_cvt_pk_bf16_f32 v17, v18, v19
	ds_write_b64 v191, v[16:17]
	v_pk_mul_f32 v[16:17], v[28:29], v[42:43] op_sel_hi:[1,0]
	v_pk_mul_f32 v[18:19], v[30:31], v[42:43] op_sel_hi:[1,0]
	v_pk_mul_f32 v[0:1], v[0:1], v[42:43] op_sel_hi:[1,0]
	v_pk_mul_f32 v[2:3], v[2:3], v[42:43] op_sel_hi:[1,0]
	v_pk_mul_f32 v[16:17], v[16:17], v[74:75]
	v_pk_mul_f32 v[18:19], v[18:19], v[76:77]
	v_pk_mul_f32 v[0:1], v[0:1], v[218:219]
	v_pk_mul_f32 v[2:3], v[2:3], v[34:35]
	v_cvt_pk_bf16_f32 v16, v16, v17
	v_cvt_pk_bf16_f32 v17, v18, v19
	v_cvt_pk_bf16_f32 v0, v0, v1
	v_cvt_pk_bf16_f32 v1, v2, v3
	v_and_b32_e32 v39, 0xffff0000, v205
	ds_write_b64 v192, v[16:17]
	ds_write_b64 v193, v[0:1]
	v_pk_mul_f32 v[0:1], v[4:5], v[42:43] op_sel_hi:[1,0]
	v_pk_mul_f32 v[2:3], v[6:7], v[42:43] op_sel_hi:[1,0]
	v_pk_mul_f32 v[0:1], v[0:1], v[36:37]
	v_pk_mul_f32 v[2:3], v[2:3], v[38:39]
	v_cvt_pk_bf16_f32 v0, v0, v1
	v_cvt_pk_bf16_f32 v1, v2, v3
	v_lshlrev_b32_e32 v40, 16, v206
	v_and_b32_e32 v41, 0xffff0000, v206
	v_lshlrev_b32_e32 v32, 16, v207
	v_and_b32_e32 v33, 0xffff0000, v207
	ds_write_b64 v194, v[0:1]
	v_pk_mul_f32 v[0:1], v[8:9], v[42:43] op_sel_hi:[1,0]
	v_pk_mul_f32 v[2:3], v[10:11], v[42:43] op_sel_hi:[1,0]
	v_pk_mul_f32 v[0:1], v[0:1], v[40:41]
	v_pk_mul_f32 v[2:3], v[2:3], v[32:33]
	v_cvt_pk_bf16_f32 v0, v0, v1
	v_cvt_pk_bf16_f32 v1, v2, v3
	ds_write_b64 v195, v[0:1]
	v_pk_mul_f32 v[0:1], v[12:13], v[42:43] op_sel_hi:[1,0]
	v_lshlrev_b32_e32 v2, 16, v208
	v_and_b32_e32 v3, 0xffff0000, v208
	v_pk_mul_f32 v[0:1], v[0:1], v[2:3]
	v_pk_mul_f32 v[2:3], v[14:15], v[42:43] op_sel_hi:[1,0]
	v_lshlrev_b32_e32 v4, 16, v209
	v_and_b32_e32 v5, 0xffff0000, v209
	v_pk_mul_f32 v[2:3], v[2:3], v[4:5]
	v_cvt_pk_bf16_f32 v0, v0, v1
	v_cvt_pk_bf16_f32 v1, v2, v3
	ds_write_b64 v196, v[0:1]
	v_mov_b32_e32 v0, v152
	s_nop 0
	v_ashrrev_i32_e32 v1, 31, v0
	v_lshrrev_b32_e32 v1, 29, v1
	v_add_u32_e32 v1, v0, v1
	v_ashrrev_i32_e32 v8, 3, v1
	v_and_b32_e32 v1, -8, v1
	v_sub_u32_e32 v0, v0, v1
	v_bitop3_b32 v1, v8, v0, 7 bitop3:0x6c
	v_lshlrev_b32_e32 v0, 3, v0
	v_lshl_add_u32 v16, v1, 4, s2
	v_ashrrev_i32_e32 v1, 31, v0
	v_lshl_add_u64 v[10:11], v[0:1], 1, s[0:1]
	v_lshl_add_u32 v0, v8, 7, v16
	v_ashrrev_i32_e32 v9, 31, v8
	ds_read_b128 v[0:3], v0
	v_lshlrev_b64 v[4:5], 11, v[8:9]
	v_add_u32_e32 v14, 8, v8
	v_lshl_add_u64 v[12:13], v[10:11], 0, v[4:5]
	v_lshl_add_u32 v4, v14, 7, v16
	ds_read_b128 v[4:7], v4
	v_ashrrev_i32_e32 v15, 31, v14
	s_waitcnt lgkmcnt(1)
	global_store_dwordx4 v[12:13], v[0:3], off
	s_nop 1
	v_lshlrev_b64 v[0:1], 11, v[14:15]
	v_lshl_add_u64 v[0:1], v[10:11], 0, v[0:1]
	s_waitcnt lgkmcnt(0)
	global_store_dwordx4 v[0:1], v[4:7], off
	s_nop 1
	v_add_u32_e32 v4, 16, v8
	v_lshl_add_u32 v0, v4, 7, v16
	v_ashrrev_i32_e32 v5, 31, v4
	ds_read_b128 v[0:3], v0
	v_lshlrev_b64 v[4:5], 11, v[4:5]
	v_add_u32_e32 v8, 24, v8
	v_lshl_add_u64 v[12:13], v[10:11], 0, v[4:5]
	v_lshl_add_u32 v4, v8, 7, v16
	ds_read_b128 v[4:7], v4
	v_ashrrev_i32_e32 v9, 31, v8
	s_waitcnt lgkmcnt(1)
	global_store_dwordx4 v[12:13], v[0:3], off
	s_nop 1
	v_lshlrev_b64 v[0:1], 11, v[8:9]
	v_lshl_add_u64 v[0:1], v[10:11], 0, v[0:1]
	s_waitcnt lgkmcnt(0)
	global_store_dwordx4 v[0:1], v[4:7], off
	s_cbranch_scc0 .LBB0_594
	v_readlane_b32 s66, v254, 22
	v_readlane_b32 s67, v254, 23

.LBB0_731:
	s_andn2_saveexec_b64 s[2:3], s[8:9]
	s_cbranch_execz .LBB0_751
	s_mov_b64 s[8:9], exec
	s_cmp_lg_u32 s98, 0
	s_cbranch_scc0 .Lxl_full_6
	s_mov_b64 s[8:9], exec
	buffer_inv sc1
	s_branch .LBB0_748
.Lxl_full_6:
	buffer_wbl2 sc1
	s_waitcnt lgkmcnt(0)
	s_waitcnt vmcnt(0)
	v_mbcnt_lo_u32_b32 v1, s8, 0
	v_mbcnt_hi_u32_b32 v1, s9, v1
	v_cmp_eq_u32_e32 vcc, 0, v1
	s_and_saveexec_b64 s[10:11], vcc
	s_cbranch_execz .LBB0_734
	s_bcnt1_i32_b64 s2, s[8:9]
	v_mov_b32_e32 v2, 0xfa03000
	v_mov_b32_e32 v3, s2
	global_atomic_add v2, v2, v3, s[74:75] offset:1024 sc0

.LBB0_776:
	s_waitcnt vmcnt(0)
	s_and_b64 vcc, exec, s[66:67]
	s_barrier
	s_cmp_eq_u32 s78, 0x100
	s_cbranch_scc1 .LBB0_831
	s_cbranch_vccnz .LBB0_831
	v_mbcnt_lo_u32_b32 v0, -1, 0
	v_mbcnt_hi_u32_b32 v0, -1, v0
	s_nop 0
	v_cmp_eq_u32_e32 vcc, 0, v0
	s_and_saveexec_b64 s[0:1], vcc
	s_cbranch_execz .LBB0_830
	s_add_i32 s2, 0, 0x21000
	v_mov_b32_e32 v0, s2
	s_waitcnt vmcnt(0) expcnt(0) lgkmcnt(0)
	ds_read_b32 v2, v0
	s_add_i32 s2, 0, 0x21004
	v_mov_b32_e32 v0, s2
	ds_read_b32 v0, v0
	s_waitcnt lgkmcnt(1)
	v_cmp_ne_u32_e32 vcc, 0, v2
	s_cbranch_vccnz .LBB0_794
	s_add_u32 s6, s74, 0xfa00200
	s_addc_u32 s7, s75, 0
	s_add_u32 s8, s74, 0xfa00400
	s_addc_u32 s9, s75, 0
	s_add_u32 s10, s74, 0xfa00500
	s_addc_u32 s11, s75, 0
	s_add_u32 s12, s74, 0xfa00600
	s_addc_u32 s13, s75, 0
	s_add_u32 s14, s74, 0xfa00700
	s_addc_u32 s15, s75, 0
	s_add_u32 s16, s74, 0xfa00800
	s_addc_u32 s17, s75, 0
	s_add_u32 s18, s74, 0xfa00900
	s_addc_u32 s19, s75, 0
	s_add_u32 s20, s74, 0xfa00a00
	s_addc_u32 s21, s75, 0
	s_add_u32 s22, s74, 0xfa00b00
	s_addc_u32 s23, s75, 0
	s_add_u32 s24, s74, 0xfa00c00
	s_addc_u32 s25, s75, 0
	s_add_u32 s26, s74, 0xfa00d00
	s_addc_u32 s27, s75, 0
	s_add_u32 s28, s74, 0xfa00e00
	s_addc_u32 s29, s75, 0
	s_add_u32 s30, s74, 0xfa00f00
	s_addc_u32 s31, s75, 0
	s_add_u32 s34, s74, 0xfa01000
	s_addc_u32 s35, s75, 0
	s_add_u32 s36, s74, 0xfa01100
	s_addc_u32 s37, s75, 0
	s_add_u32 s38, s74, 0xfa01200
	v_readlane_b32 s2, v254, 4
	s_addc_u32 s39, s75, 0
	s_mul_i32 s2, s79, s2
	s_add_u32 s46, s74, 0xfa01300
	s_mul_i32 s2, s2, s78
	s_addc_u32 s47, s75, 0
	s_mov_b32 s3, 1
	v_mov_b32_e32 v16, 0
	s_branch .LBB0_782

.LBB0_831:
	v_readlane_b32 s8, v254, 28
	s_waitcnt lgkmcnt(0)
	s_barrier
	v_mbcnt_lo_u32_b32 v144, -1, 0
	v_mbcnt_hi_u32_b32 v144, -1, v144
	v_readlane_b32 s16, v254, 36
	v_ashrrev_i32_e32 v145, 31, v144
	v_readlane_b32 s17, v254, 37
	v_readlane_b32 s18, v254, 38
	v_readlane_b32 s19, v254, 39
	v_readlane_b32 s20, v254, 40
	v_readlane_b32 s21, v254, 41
	v_lshlrev_b64 v[0:1], 2, v[144:145]
	v_readlane_b32 s22, v254, 42
	v_readlane_b32 s23, v254, 43
	s_mov_b64 s[16:17], s[20:21]
	s_mov_b64 s[18:19], s[22:23]
	v_lshl_add_u64 v[2:3], s[16:17], 0, v[0:1]
	v_lshl_add_u64 v[0:1], s[18:19], 0, v[0:1]
	global_load_dword v4, v[2:3], off
	global_load_dword v5, v[2:3], off offset:256
	global_load_dword v6, v[2:3], off offset:512
	global_load_dword v7, v[2:3], off offset:768
	global_load_dword v8, v[0:1], off
	global_load_dword v9, v[0:1], off offset:256
	global_load_dword v10, v[0:1], off offset:512
	global_load_dword v11, v[0:1], off offset:768
	s_add_u32 s2, s74, 0x6600000
	s_mov_b32 s1, 0
	s_addc_u32 s3, s75, 0
	s_and_b64 vcc, exec, s[4:5]
	v_readlane_b32 s9, v254, 29
	v_readlane_b32 s10, v254, 30
	v_readlane_b32 s11, v254, 31
	v_readlane_b32 s12, v254, 32
	v_readlane_b32 s13, v254, 33
	v_readlane_b32 s14, v254, 34
	v_readlane_b32 s15, v254, 35
	s_waitcnt vmcnt(0)
	v_max3_f32 v0, |v4|, 0, |v5|
	v_mov_b32_e32 v4, 0xc2700000
	v_max3_f32 v0, v0, |v6|, |v7|
	ds_swizzle_b32 v2, v0 offset:swizzle(SWAP,1)
	v_max3_f32 v1, |v8|, 0, |v9|
	v_max3_f32 v1, v1, |v10|, |v11|
	ds_swizzle_b32 v3, v1 offset:swizzle(SWAP,1)
	s_waitcnt lgkmcnt(1)
	v_max_f32_e32 v2, v2, v2
	v_max_f32_e32 v0, v0, v2
	ds_swizzle_b32 v2, v0 offset:swizzle(SWAP,2)
	s_waitcnt lgkmcnt(1)
	v_max_f32_e32 v3, v3, v3
	v_max_f32_e32 v1, v1, v3
	ds_swizzle_b32 v3, v1 offset:swizzle(SWAP,2)
	s_waitcnt lgkmcnt(1)
	v_max_f32_e32 v2, v2, v2
	v_max_f32_e32 v0, v0, v2
	ds_swizzle_b32 v2, v0 offset:swizzle(SWAP,4)
	s_waitcnt lgkmcnt(1)
	v_max_f32_e32 v3, v3, v3
	v_max_f32_e32 v1, v1, v3
	ds_swizzle_b32 v3, v1 offset:swizzle(SWAP,4)
	s_waitcnt lgkmcnt(1)
	v_max_f32_e32 v2, v2, v2
	v_max_f32_e32 v0, v0, v2
	ds_swizzle_b32 v2, v0 offset:swizzle(SWAP,8)
	s_waitcnt lgkmcnt(1)
	v_max_f32_e32 v3, v3, v3
	v_max_f32_e32 v1, v1, v3
	ds_swizzle_b32 v3, v1 offset:swizzle(SWAP,8)
	s_waitcnt lgkmcnt(1)
	v_max_f32_e32 v2, v2, v2
	v_max_f32_e32 v0, v0, v2
	ds_swizzle_b32 v2, v0 offset:swizzle(SWAP,16)
	s_waitcnt lgkmcnt(1)
	v_max_f32_e32 v3, v3, v3
	v_max_f32_e32 v1, v1, v3
	ds_swizzle_b32 v3, v1 offset:swizzle(SWAP,16)
	s_waitcnt lgkmcnt(1)
	v_max_f32_e32 v2, v2, v2
	v_max_f32_e32 v0, v0, v2
	v_mov_b32_e32 v2, v0
	s_nop 1
	v_permlane32_swap_b32_e32 v0, v2
	s_waitcnt lgkmcnt(0)
	v_max_f32_e32 v3, v3, v3
	v_max_f32_e32 v1, v1, v3
	v_mov_b32_e32 v3, v1
	s_nop 1
	v_permlane32_swap_b32_e32 v1, v3
	v_max_f32_e32 v2, v2, v2
	v_max_f32_e32 v0, v0, v0
	v_max_f32_e32 v3, v3, v3
	v_max_f32_e32 v1, v1, v1
	v_max_f32_e32 v0, v0, v2
	v_max_f32_e32 v1, v1, v3
	v_mul_f32_e32 v0, v0, v1
	v_mul_f32_e32 v0, 0x43800000, v0
	v_fmac_f32_e32 v4, 0x3db8aa3b, v0
	v_max_f32_e32 v0, 0, v4
	s_nop 0
	v_readfirstlane_b32 s7, v0
	s_cbranch_vccnz .LBB0_844
	v_readlane_b32 s0, v254, 44
	v_and_b32_e32 v4, 7, v144
	v_readlane_b32 s4, v254, 45
	v_add_u32_e32 v2, s0, v144
	v_lshlrev_b32_e32 v3, 2, v144
	s_add_i32 s0, 0, 0x20000
	v_mov_b32_e32 v149, 0
	v_lshlrev_b32_e32 v148, 4, v4
	v_readlane_b32 s5, v254, 46
	v_readlane_b32 s8, v254, 52
	v_and_b32_e32 v1, 31, v144
	v_add_u32_e32 v161, s0, v3
	v_lshl_add_u64 v[150:151], s[4:5], 0, v[148:149]
	s_add_i32 s0, 0, 0x10000
	s_lshl_b32 s4, s8, 14
	s_add_i32 s4, s0, s4
	v_lshlrev_b32_e32 v7, 9, v1
	v_add_u32_e32 v166, s4, v7
	v_lshlrev_b32_e32 v9, 4, v144
	s_movk_i32 s4, 0x70
	v_ashrrev_i32_e32 v146, 3, v2
	v_bitop3_b32 v2, v2, s4, v9 bitop3:0x48
	v_and_b32_e32 v9, 19, v144
	v_lshlrev_b32_e32 v10, 1, v144
	v_lshrrev_b32_e32 v11, 1, v144
	v_readlane_b32 s5, v254, 48
	v_and_b32_e32 v10, 8, v10
	v_and_or_b32 v9, v11, 4, v9
	s_lshl_b32 s4, s5, 14
	v_or_b32_e32 v12, v9, v10
	s_add_i32 s4, s4, 0
	v_readlane_b32 s6, v254, 25
	v_ashrrev_i32_e32 v145, 5, v144
	v_lshl_add_u32 v168, v12, 9, s4
	s_and_b32 s4, s6, 0x3fffffc
	v_bitop3_b32 v169, v9, 15, v10 bitop3:0xc8
	v_add_u32_e32 v9, s4, v145
	s_lshl_b32 s4, s8, 15
	s_add_i32 s11, s4, 0
	v_lshlrev_b32_e32 v5, 9, v146
	v_add_u32_e32 v171, s11, v3
	v_lshlrev_b32_e32 v3, 3, v145
	v_and_b32_e32 v6, 0x3e00, v5
	v_add3_u32 v172, s11, v7, v3
	v_and_b32_e32 v3, 0xffffc000, v5
	v_add3_u32 v173, s0, v6, v3
	v_bitop3_b32 v3, v146, v4, 15 bitop3:0x6c
	v_lshlrev_b32_e32 v148, 5, v4
	v_lshlrev_b32_e32 v174, 4, v3
	v_or_b32_e32 v3, 8, v4
	v_lshl_add_u64 v[152:153], s[16:17], 0, v[148:149]
	v_lshlrev_b32_e32 v148, 5, v3
	v_bitop3_b32 v3, v146, v3, 15 bitop3:0x6c
	v_lshlrev_b32_e32 v175, 4, v3
	v_or_b32_e32 v3, 16, v4
	v_lshl_add_u64 v[154:155], s[16:17], 0, v[148:149]
	v_lshlrev_b32_e32 v148, 5, v3
	v_bitop3_b32 v3, v146, v3, 15 bitop3:0x6c
	v_lshlrev_b32_e32 v176, 4, v3
	v_or_b32_e32 v3, 24, v4
	v_lshlrev_b32_e32 v0, 3, v4
	v_lshl_add_u64 v[156:157], s[16:17], 0, v[148:149]
	v_lshlrev_b32_e32 v148, 5, v3
	v_bitop3_b32 v3, v146, v3, 15 bitop3:0x6c
	v_add_u32_e32 v4, 2, v9
	v_lshlrev_b32_e32 v177, 4, v3
	v_bitop3_b32 v3, v9, v11, 7 bitop3:0x78
	v_bitop3_b32 v4, v4, v11, 7 bitop3:0x78
	v_lshlrev_b32_e32 v178, 4, v1
	v_add_u32_e32 v167, 0, v5
	v_lshl_add_u32 v8, v146, 7, 0
	v_lshl_add_u32 v10, v1, 7, 0
	s_cmp_eq_u32 s5, 1
	v_lshlrev_b32_e32 v3, 4, v3
	v_lshlrev_b32_e32 v4, 4, v4
	v_xor_b32_e32 v1, 16, v178
	v_xor_b32_e32 v5, 32, v178
	v_xor_b32_e32 v6, 48, v178
	v_xor_b32_e32 v7, 64, v178
	v_xor_b32_e32 v9, 0x50, v178
	v_xor_b32_e32 v11, 0x60, v178
	v_xor_b32_e32 v12, 0x70, v178
	v_xor_b32_e32 v13, 0x80, v178
	v_xor_b32_e32 v14, 0x90, v178
	v_xor_b32_e32 v15, 0xa0, v178
	v_xor_b32_e32 v16, 0xb0, v178
	v_xor_b32_e32 v17, 0xc0, v178
	v_xor_b32_e32 v18, 0xd0, v178
	v_xor_b32_e32 v19, 0xe0, v178
	v_xor_b32_e32 v20, 0xf0, v178
	v_xor_b32_e32 v21, 0x100, v178
	v_xor_b32_e32 v22, 0x110, v178
	v_xor_b32_e32 v23, 0x120, v178
	v_xor_b32_e32 v24, 0x130, v178
	v_xor_b32_e32 v25, 0x140, v178
	v_xor_b32_e32 v26, 0x150, v178
	v_xor_b32_e32 v27, 0x160, v178
	v_xor_b32_e32 v28, 0x170, v178
	v_xor_b32_e32 v29, 0x180, v178
	v_xor_b32_e32 v30, 0x190, v178
	v_xor_b32_e32 v31, 0x1a0, v178
	v_xor_b32_e32 v32, 0x1b0, v178
	v_xor_b32_e32 v33, 0x1c0, v178
	v_xor_b32_e32 v34, 0x1d0, v178
	v_xor_b32_e32 v35, 0x1e0, v178
	v_xor_b32_e32 v36, 0x1f0, v178
	s_mov_b32 s10, 0x20000
	v_ashrrev_i32_e32 v147, 31, v146
	v_and_b32_e32 v170, 15, v144
	s_cselect_b64 s[4:5], -1, 0
	s_lshl_b32 s12, s8, 8
	s_lshl_b32 s13, s6, 8
	v_lshl_add_u64 v[158:159], s[16:17], 0, v[148:149]
	s_mov_b32 s6, 0x3b800000
	s_mov_b32 s14, 0x800000
	v_lshlrev_b32_e32 v148, 1, v0
	v_add_u32_e32 v179, v8, v2
	v_add_u32_e32 v180, v10, v3
	v_add_u32_e32 v181, v10, v4
	v_add_u32_e32 v182, v172, v1
	v_add_u32_e32 v183, v172, v5
	v_add_u32_e32 v184, v172, v6
	v_add_u32_e32 v185, v172, v7
	v_add_u32_e32 v186, v172, v9
	v_add_u32_e32 v187, v172, v11
	v_add_u32_e32 v188, v172, v12
	v_add_u32_e32 v189, v172, v13
	v_add_u32_e32 v190, v172, v14
	v_add_u32_e32 v191, v172, v15
	v_add_u32_e32 v192, v172, v16
	v_add_u32_e32 v193, v172, v17
	v_add_u32_e32 v194, v172, v18
	v_add_u32_e32 v195, v172, v19
	v_add_u32_e32 v196, v172, v20
	v_add_u32_e32 v197, v172, v21
	v_add_u32_e32 v198, v172, v22
	v_add_u32_e32 v199, v172, v23
	v_add_u32_e32 v200, v172, v24
	v_add_u32_e32 v201, v172, v25
	v_add_u32_e32 v202, v172, v26
	v_add_u32_e32 v203, v172, v27
	v_add_u32_e32 v204, v172, v28
	v_add_u32_e32 v205, v172, v29
	v_add_u32_e32 v206, v172, v30
	v_add_u32_e32 v207, v172, v31
	v_add_u32_e32 v208, v172, v32
	v_add_u32_e32 v209, v172, v33
	v_add_u32_e32 v210, v172, v34
	v_add_u32_e32 v211, v172, v35
	v_add_u32_e32 v212, v172, v36
	v_mov_b32_e32 v160, 0x358637bd
	s_mov_b32 s15, s70
	s_cmp_eq_u32 s78, 0x100
	s_cbranch_scc0 .LBB0_834
	s_and_b32 s15, s70, 7
	s_lshr_b32 s16, s15, 2
	s_lshl_b32 s16, s16, 8
	s_and_b32 s15, s15, 3
	s_lshl_b32 s15, s15, 4
	s_or_b32 s15, s15, s16
	s_lshr_b32 s16, s70, 3
	s_and_b32 s16, s16, 7
	s_lshl_b32 s16, s16, 1
	s_or_b32 s15, s15, s16
	s_lshr_b32 s16, s70, 6
	s_lshl_b32 s16, s16, 6
	s_or_b32 s15, s15, s16
	s_branch .LBB0_834
.LBB0_833:
	s_cmp_eq_u32 s78, 0x100
	s_cbranch_scc0 .Lp7_orig_inc
	s_add_i32 s15, s15, 1
	s_bitcmp1_b32 s15, 0
	s_cbranch_scc0 .LBB0_844
	s_branch .LBB0_834

.LBB0_877:
	s_andn2_saveexec_b64 s[6:7], s[6:7]
	s_cbranch_execz .LBB0_897
	s_mov_b64 s[6:7], exec
	s_cmp_lg_u32 s98, 0
	s_cbranch_scc0 .Lxl_full_8
	s_mov_b64 s[6:7], exec
	buffer_inv sc1
	s_branch .LBB0_894
.Lxl_full_8:
	buffer_wbl2 sc1
	s_waitcnt lgkmcnt(0)
	s_waitcnt vmcnt(0)
	v_mbcnt_lo_u32_b32 v1, s6, 0
	v_mbcnt_hi_u32_b32 v1, s7, v1
	v_cmp_eq_u32_e32 vcc, 0, v1
	s_and_saveexec_b64 s[8:9], vcc
	s_cbranch_execz .LBB0_880
	s_bcnt1_i32_b64 s6, s[6:7]
	v_mov_b32_e32 v2, 0xfa03000
	v_mov_b32_e32 v3, s6
	global_atomic_add v2, v2, v3, s[74:75] offset:1024 sc0

.LBB0_973:
	s_andn2_saveexec_b64 s[2:3], s[6:7]
	s_cbranch_execz .LBB0_993
	s_mov_b64 s[6:7], exec
	s_cmp_lg_u32 s98, 0
	s_cbranch_scc0 .Lxl_full_9
	s_mov_b64 s[6:7], exec
	buffer_inv sc1
	s_branch .LBB0_990
.Lxl_full_9:
	buffer_wbl2 sc1
	s_waitcnt lgkmcnt(0)
	s_waitcnt vmcnt(0)
	v_mbcnt_lo_u32_b32 v1, s6, 0
	v_mbcnt_hi_u32_b32 v1, s7, v1
	v_cmp_eq_u32_e32 vcc, 0, v1
	s_and_saveexec_b64 s[10:11], vcc
	s_cbranch_execz .LBB0_976
	s_bcnt1_i32_b64 s2, s[6:7]
	v_mov_b32_e32 v2, 0xfa03000
	v_mov_b32_e32 v3, s2
	global_atomic_add v2, v2, v3, s[74:75] offset:1024 sc0

.Lxl_full_10:
	buffer_wbl2 sc1
	s_waitcnt lgkmcnt(0)
	s_waitcnt vmcnt(0)
	v_mbcnt_lo_u32_b32 v1, s6, 0
	v_mbcnt_hi_u32_b32 v1, s7, v1
	v_cmp_eq_u32_e32 vcc, 0, v1
	s_and_saveexec_b64 s[8:9], vcc
	s_cbranch_execz .LBB0_1046
	s_bcnt1_i32_b64 s2, s[6:7]
	v_mov_b32_e32 v2, 0xfa03000
	v_mov_b32_e32 v3, s2
	global_atomic_add v2, v2, v3, s[74:75] offset:1024 sc0
